# GEMM K-loop: one static priority raise for the trailing wave half, per-phase s_setprio flips removed
# baseline (speedup 1.0000x reference)
.LBB0_206:
	s_andn2_b64 vcc, exec, s[2:3]
	s_cbranch_vccnz .LBB0_1296
	s_waitcnt lgkmcnt(0)
	v_bfe_i32 v3, v19, 27, 1
	v_lshlrev_b32_e32 v1, 4, v19
	v_lshrrev_b32_e32 v3, 22, v3
	v_add_u32_e32 v3, v1, v3
	v_and_b32_e32 v3, 0xfffffc00, v3
	v_sub_u32_e32 v3, v1, v3
	v_ashrrev_i32_e32 v2, 31, v19
	v_lshrrev_b32_e32 v4, 4, v3
	v_lshrrev_b32_e32 v2, 26, v2
	v_bitop3_b32 v3, v4, v3, 32 bitop3:0x6c
	v_add_u32_e32 v2, v19, v2
	v_ashrrev_i32_e32 v5, 31, v3
	v_ashrrev_i32_e32 v2, 6, v2
	v_lshrrev_b32_e32 v5, 26, v5
	v_lshlrev_b32_e32 v4, 3, v2
	v_add_u32_e32 v5, v3, v5
	v_and_b32_e32 v4, -16, v4
	v_ashrrev_i32_e32 v6, 6, v5
	v_lshlrev_b32_e32 v2, 5, v2
	v_add_u32_e32 v4, v6, v4
	v_and_b32_e32 v14, 32, v2
	v_and_b32_e32 v2, 0xc0, v5
	v_sub_u32_e32 v2, v3, v2
	v_lshlrev_b32_e32 v3, 1, v4
	v_lshrrev_b32_e32 v5, 2, v4
	v_and_b32_e32 v6, 3, v6
	s_mov_b32 s3, 0x7fffffe0
	v_ashrrev_i16_sdwa v2, v208, sext(v2) dst_sel:DWORD dst_unused:UNUSED_PAD src0_sel:DWORD src1_sel:BYTE_0
	v_and_b32_e32 v3, 24, v3
	v_and_b32_e32 v5, 4, v5
	v_and_or_b32 v6, v4, s3, v6
	v_bfe_i32 v15, v2, 0, 16
	v_or3_b32 v3, v6, v5, v3
	v_add_u32_e32 v2, v14, v15
	v_mul_lo_u32 v16, v4, s17
	v_mul_lo_u32 v3, v3, s17
	v_add_u32_e32 v1, 0x2000, v1
	s_waitcnt vmcnt(8)
	v_add_lshl_u32 v130, v2, v16, 1
	v_add_lshl_u32 v132, v3, v2, 1
	v_ashrrev_i32_e32 v2, 31, v1
	v_lshrrev_b32_e32 v2, 22, v2
	v_add_u32_e32 v2, v1, v2
	v_ashrrev_i32_e32 v2, 10, v2
	v_mul_i32_i24_e32 v3, 0x400, v2
	v_sub_u32_e32 v1, v1, v3
	s_lshl_b32 s56, s17, 8
	s_mov_b32 s57, s85
	v_lshrrev_b32_e32 v3, 4, v1
	s_lshl_b64 s[58:59], s[56:57], 1
	s_ashr_i32 s4, s14, 31
	v_bitop3_b32 v1, v3, v1, 32 bitop3:0x6c
	s_mul_i32 s4, s58, s4
	s_mul_hi_u32 s5, s58, s14
	v_ashrrev_i32_e32 v4, 31, v1
	s_add_i32 s4, s5, s4
	s_bfe_u32 s5, s17, 0x10017
	v_lshrrev_b32_e32 v4, 26, v4
	s_mul_i32 s6, s5, s14
	v_lshlrev_b32_e32 v3, 3, v2
	v_add_u32_e32 v4, v1, v4
	s_add_i32 s11, s4, s6
	s_ashr_i32 s4, s13, 31
	v_writelane_b32 v243, s36, 39
	v_and_b32_e32 v3, -16, v3
	v_ashrrev_i32_e32 v5, 6, v4
	s_mul_i32 s4, s58, s4
	s_mul_hi_u32 s6, s58, s13
	v_writelane_b32 v243, s37, 40
	s_ashr_i32 s2, s15, 6
	v_add_u32_e32 v3, v5, v3
	v_lshlrev_b32_e32 v2, 5, v2
	v_and_b32_e32 v5, 3, v5
	s_add_i32 s4, s6, s4
	s_mul_i32 s5, s5, s13
	v_and_b32_e32 v17, 32, v2
	v_and_b32_e32 v2, 0xc0, v4
	v_and_or_b32 v5, v3, s3, v5
	s_ashr_i32 s3, s15, 8
	s_lshl_b32 s74, s2, 10
	s_add_i32 s4, s4, s5
	s_mul_i32 s5, s58, s13
	v_readlane_b32 s6, v243, 37
	v_sub_u32_e32 v1, v1, v2
	v_lshlrev_b32_e32 v2, 1, v3
	v_lshrrev_b32_e32 v4, 2, v3
	v_readlane_b32 s7, v243, 38
	s_add_u32 s6, s6, s5
	v_ashrrev_i16_sdwa v1, v208, sext(v1) dst_sel:DWORD dst_unused:UNUSED_PAD src0_sel:DWORD src1_sel:BYTE_0
	v_and_b32_e32 v2, 24, v2
	v_and_b32_e32 v4, 4, v4
	s_addc_u32 s7, s7, s4
	s_add_i32 s75, s74, 0
	v_bfe_i32 v18, v1, 0, 16
	v_or3_b32 v2, v5, v4, v2
	s_add_i32 m0, s75, 0x10000
	v_add_u32_e32 v1, v17, v18
	v_mul_lo_u32 v2, v2, s17
	global_load_lds_dwordx4 v132, s[6:7]
	s_add_i32 m0, s75, 0x12000
	v_add_lshl_u32 v136, v2, v1, 1
	s_add_u32 s4, s6, s56
	global_load_lds_dwordx4 v136, s[6:7]
	s_addc_u32 s5, s7, 0
	s_add_i32 m0, s75, 0x14000
	v_mov_b32_e32 v133, v0
	v_mov_b32_e32 v137, v0
	global_load_lds_dwordx4 v132, s[4:5]
	s_add_i32 m0, s75, 0x16000
	s_mul_i32 s10, s58, s14
	v_lshl_add_u64 v[6:7], s[4:5], 0, v[132:133]
	v_lshl_add_u64 v[8:9], s[4:5], 0, v[136:137]
	global_load_lds_dwordx4 v136, s[4:5]
	v_readlane_b32 s4, v243, 35
	v_readlane_b32 s5, v243, 36
	s_add_u32 s10, s4, s10
	s_addc_u32 s11, s5, s11
	s_add_i32 s60, s75, 0x2000
	v_mul_lo_u32 v20, v3, s17
	s_mov_b32 m0, s75
	s_add_u32 s4, s10, s56
	v_add_lshl_u32 v134, v1, v20, 1
	global_load_lds_dwordx4 v130, s[10:11]
	s_mov_b32 m0, s60
	s_addc_u32 s5, s11, 0
	s_add_i32 s61, s75, 0x4000
	global_load_lds_dwordx4 v134, s[10:11]
	s_mov_b32 m0, s61
	s_add_i32 s46, s75, 0x6000
	global_load_lds_dwordx4 v130, s[4:5]
	s_mov_b32 m0, s46
	s_cmp_eq_u32 s3, 1
	global_load_lds_dwordx4 v134, s[4:5]
	v_mov_b32_e32 v131, v0
	v_mov_b32_e32 v135, v0
	s_cselect_b64 s[4:5], -1, 0
	v_lshl_add_u64 v[2:3], s[6:7], 0, v[132:133]
	v_lshl_add_u64 v[4:5], s[6:7], 0, v[136:137]
	v_lshl_add_u64 v[10:11], s[10:11], 0, v[130:131]
	v_lshl_add_u64 v[12:13], s[10:11], 0, v[134:135]
	v_writelane_b32 v243, s4, 41
	s_cmp_lg_u32 s3, 1
	s_nop 0
	v_writelane_b32 v243, s5, 42
	s_cbranch_scc1 .LBB0_209
	s_setprio 1
	s_barrier

.LBB0_223:
	s_add_i32 s10, s8, 2
	s_add_u32 s11, s6, 0x80
	s_addc_u32 s9, s7, 0
	s_add_i32 s17, 0, 0x10000
	s_cmp_eq_u32 s45, s8
	s_cselect_b32 s9, s73, s9
	s_cselect_b32 s8, s72, s11
	s_cselect_b32 s19, s5, s16
	s_cselect_b32 s18, s4, s15
	s_add_i32 s11, 0, 0x14000
	v_add_u32_e32 v156, s17, v191
	v_add_u32_e32 v172, s11, v191
	ds_read_b128 v[144:147], v156
	ds_read_b128 v[148:151], v156 offset:1024
	ds_read_b128 v[152:155], v156 offset:2048
	ds_read_b128 v[156:159], v156 offset:3072
	ds_read_b128 v[160:163], v172
	ds_read_b128 v[164:167], v172 offset:1024
	ds_read_b128 v[168:171], v172 offset:2048
	ds_read_b128 v[172:175], v172 offset:3072
	v_lshl_add_u64 v[188:189], s[6:7], 0, v[140:141]
	s_add_i32 m0, s75, 0xc000
	ds_read_b128 v[176:179], v193
	ds_read_b128 v[180:183], v193 offset:1024
	ds_read_b128 v[184:187], v193 offset:2048
	ds_read_b128 v[194:197], v193 offset:3072
	ds_read_b128 v[198:201], v193 offset:4096
	ds_read_b128 v[204:207], v193 offset:5120
	ds_read_b128 v[214:217], v193 offset:6144
	ds_read_b128 v[218:221], v193 offset:7168
	global_load_lds_dwordx4 v[188:189], off
	v_lshl_add_u64 v[188:189], s[6:7], 0, v[138:139]
	s_add_i32 m0, s75, 0xe000
	s_nop 0
	global_load_lds_dwordx4 v[188:189], off
	s_waitcnt vmcnt(8)
	s_waitcnt lgkmcnt(0)
	s_barrier
	s_waitcnt lgkmcnt(0)
	v_mfma_f32_16x16x32_bf16 v[126:129], v[144:147], v[176:179], v[126:129]
	v_mfma_f32_16x16x32_bf16 v[122:125], v[152:155], v[176:179], v[122:125]
	v_mfma_f32_16x16x32_bf16 v[110:113], v[144:147], v[184:187], v[110:113]
	v_mfma_f32_16x16x32_bf16 v[106:109], v[152:155], v[184:187], v[106:109]
	v_mfma_f32_16x16x32_bf16 v[94:97], v[144:147], v[198:201], v[94:97]
	v_mfma_f32_16x16x32_bf16 v[90:93], v[152:155], v[198:201], v[90:93]
	v_mfma_f32_16x16x32_bf16 v[78:81], v[144:147], v[214:217], v[78:81]
	v_mfma_f32_16x16x32_bf16 v[74:77], v[152:155], v[214:217], v[74:77]
	v_mfma_f32_16x16x32_bf16 v[126:129], v[148:151], v[180:183], v[126:129]
	v_mfma_f32_16x16x32_bf16 v[122:125], v[156:159], v[180:183], v[122:125]
	v_mfma_f32_16x16x32_bf16 v[110:113], v[148:151], v[194:197], v[110:113]
	v_mfma_f32_16x16x32_bf16 v[106:109], v[156:159], v[194:197], v[106:109]
	v_mfma_f32_16x16x32_bf16 v[94:97], v[148:151], v[204:207], v[94:97]
	v_mfma_f32_16x16x32_bf16 v[90:93], v[156:159], v[204:207], v[90:93]
	v_mfma_f32_16x16x32_bf16 v[78:81], v[148:151], v[218:221], v[78:81]
	v_mfma_f32_16x16x32_bf16 v[74:77], v[156:159], v[218:221], v[74:77]
	v_mfma_f32_16x16x32_bf16 v[118:121], v[160:163], v[176:179], v[118:121]
	v_mfma_f32_16x16x32_bf16 v[114:117], v[168:171], v[176:179], v[114:117]
	v_mfma_f32_16x16x32_bf16 v[102:105], v[160:163], v[184:187], v[102:105]
	v_mfma_f32_16x16x32_bf16 v[98:101], v[168:171], v[184:187], v[98:101]
	v_mfma_f32_16x16x32_bf16 v[86:89], v[160:163], v[198:201], v[86:89]
	v_mfma_f32_16x16x32_bf16 v[82:85], v[168:171], v[198:201], v[82:85]
	v_mfma_f32_16x16x32_bf16 v[70:73], v[160:163], v[214:217], v[70:73]
	v_mfma_f32_16x16x32_bf16 v[66:69], v[168:171], v[214:217], v[66:69]
	v_mfma_f32_16x16x32_bf16 v[118:121], v[164:167], v[180:183], v[118:121]
	v_mfma_f32_16x16x32_bf16 v[114:117], v[172:175], v[180:183], v[114:117]
	v_mfma_f32_16x16x32_bf16 v[102:105], v[164:167], v[194:197], v[102:105]
	v_mfma_f32_16x16x32_bf16 v[98:101], v[172:175], v[194:197], v[98:101]
	v_mfma_f32_16x16x32_bf16 v[86:89], v[164:167], v[204:207], v[86:89]
	v_mfma_f32_16x16x32_bf16 v[82:85], v[172:175], v[204:207], v[82:85]
	v_mfma_f32_16x16x32_bf16 v[70:73], v[164:167], v[218:221], v[70:73]
	v_mfma_f32_16x16x32_bf16 v[66:69], v[172:175], v[218:221], v[66:69]
	s_barrier
	s_add_i32 s17, s17, s74
	v_lshl_add_u64 v[188:189], s[18:19], 0, v[132:133]
	s_mov_b32 m0, s17
	ds_read_b128 v[176:179], v193 offset:16384
	ds_read_b128 v[180:183], v193 offset:17408
	ds_read_b128 v[184:187], v193 offset:18432
	ds_read_b128 v[194:197], v193 offset:19456
	ds_read_b128 v[198:201], v193 offset:20480
	ds_read_b128 v[204:207], v193 offset:21504
	ds_read_b128 v[214:217], v193 offset:22528
	ds_read_b128 v[218:221], v193 offset:23552
	global_load_lds_dwordx4 v[188:189], off
	s_add_i32 m0, s17, 0x2000
	v_lshl_add_u64 v[222:223], s[18:19], 0, v[136:137]
	s_add_u32 s18, s18, s56
	s_addc_u32 s19, s19, 0
	s_add_i32 s11, s11, s74
	global_load_lds_dwordx4 v[222:223], off
	v_lshl_add_u64 v[224:225], s[18:19], 0, v[132:133]
	s_mov_b32 m0, s11
	v_lshl_add_u64 v[226:227], s[18:19], 0, v[136:137]
	global_load_lds_dwordx4 v[224:225], off
	s_add_i32 m0, s11, 0x2000
	v_lshl_add_u64 v[228:229], s[8:9], 0, v[130:131]
	global_load_lds_dwordx4 v[226:227], off
	s_mov_b32 m0, s75
	v_lshl_add_u64 v[230:231], s[8:9], 0, v[134:135]
	global_load_lds_dwordx4 v[228:229], off
	s_mov_b32 m0, s60
	s_nop 0
	global_load_lds_dwordx4 v[230:231], off
	s_waitcnt vmcnt(8)
	s_waitcnt lgkmcnt(0)
	s_barrier
	s_waitcnt lgkmcnt(0)
	v_mfma_f32_16x16x32_bf16 v[62:65], v[144:147], v[176:179], v[62:65]
	v_mfma_f32_16x16x32_bf16 v[58:61], v[152:155], v[176:179], v[58:61]
	v_mfma_f32_16x16x32_bf16 v[46:49], v[144:147], v[184:187], v[46:49]
	v_mfma_f32_16x16x32_bf16 v[42:45], v[152:155], v[184:187], v[42:45]
	v_mfma_f32_16x16x32_bf16 v[30:33], v[144:147], v[198:201], v[30:33]
	v_mfma_f32_16x16x32_bf16 v[26:29], v[152:155], v[198:201], v[26:29]
	v_mfma_f32_16x16x32_bf16 v[14:17], v[144:147], v[214:217], v[14:17]
	v_mfma_f32_16x16x32_bf16 v[10:13], v[152:155], v[214:217], v[10:13]
	v_mfma_f32_16x16x32_bf16 v[62:65], v[148:151], v[180:183], v[62:65]
	v_mfma_f32_16x16x32_bf16 v[58:61], v[156:159], v[180:183], v[58:61]
	v_mfma_f32_16x16x32_bf16 v[46:49], v[148:151], v[194:197], v[46:49]
	v_mfma_f32_16x16x32_bf16 v[42:45], v[156:159], v[194:197], v[42:45]
	v_mfma_f32_16x16x32_bf16 v[30:33], v[148:151], v[204:207], v[30:33]
	v_mfma_f32_16x16x32_bf16 v[26:29], v[156:159], v[204:207], v[26:29]
	v_mfma_f32_16x16x32_bf16 v[14:17], v[148:151], v[218:221], v[14:17]
	v_mfma_f32_16x16x32_bf16 v[10:13], v[156:159], v[218:221], v[10:13]
	v_mfma_f32_16x16x32_bf16 v[54:57], v[160:163], v[176:179], v[54:57]
	v_mfma_f32_16x16x32_bf16 v[50:53], v[168:171], v[176:179], v[50:53]
	v_mfma_f32_16x16x32_bf16 v[38:41], v[160:163], v[184:187], v[38:41]
	v_mfma_f32_16x16x32_bf16 v[34:37], v[168:171], v[184:187], v[34:37]
	v_mfma_f32_16x16x32_bf16 v[22:25], v[160:163], v[198:201], v[22:25]
	v_mfma_f32_16x16x32_bf16 v[18:21], v[168:171], v[198:201], v[18:21]
	v_mfma_f32_16x16x32_bf16 v[6:9], v[160:163], v[214:217], v[6:9]
	v_mfma_f32_16x16x32_bf16 v[2:5], v[168:171], v[214:217], v[2:5]
	v_mfma_f32_16x16x32_bf16 v[54:57], v[164:167], v[180:183], v[54:57]
	v_mfma_f32_16x16x32_bf16 v[50:53], v[172:175], v[180:183], v[50:53]
	v_mfma_f32_16x16x32_bf16 v[38:41], v[164:167], v[194:197], v[38:41]
	v_mfma_f32_16x16x32_bf16 v[34:37], v[172:175], v[194:197], v[34:37]
	v_mfma_f32_16x16x32_bf16 v[22:25], v[164:167], v[204:207], v[22:25]
	v_mfma_f32_16x16x32_bf16 v[18:21], v[172:175], v[204:207], v[18:21]
	v_mfma_f32_16x16x32_bf16 v[6:9], v[164:167], v[218:221], v[6:9]
	v_mfma_f32_16x16x32_bf16 v[2:5], v[172:175], v[218:221], v[2:5]
	s_barrier
	s_add_i32 s11, 0, 0x18000
	s_add_i32 s17, 0, 0x1c000
	v_add_u32_e32 v156, s11, v191
	v_add_u32_e32 v172, s17, v191
	ds_read_b128 v[144:147], v156
	ds_read_b128 v[148:151], v156 offset:1024
	ds_read_b128 v[152:155], v156 offset:2048
	ds_read_b128 v[156:159], v156 offset:3072
	ds_read_b128 v[160:163], v172
	ds_read_b128 v[164:167], v172 offset:1024
	ds_read_b128 v[168:171], v172 offset:2048
	ds_read_b128 v[172:175], v172 offset:3072
	s_add_u32 s8, s8, s56
	s_addc_u32 s9, s9, 0
	s_mov_b32 m0, s61
	v_lshl_add_u64 v[232:233], s[8:9], 0, v[130:131]
	ds_read_b128 v[176:179], v193 offset:32768
	ds_read_b128 v[180:183], v193 offset:33792
	ds_read_b128 v[184:187], v193 offset:34816
	ds_read_b128 v[194:197], v193 offset:35840
	ds_read_b128 v[198:201], v193 offset:36864
	ds_read_b128 v[204:207], v193 offset:37888
	ds_read_b128 v[214:217], v193 offset:38912
	ds_read_b128 v[218:221], v193 offset:39936
	global_load_lds_dwordx4 v[232:233], off
	v_lshl_add_u64 v[232:233], s[8:9], 0, v[134:135]
	s_mov_b32 m0, s46
	s_nop 0
	global_load_lds_dwordx4 v[232:233], off
	s_waitcnt vmcnt(8)
	s_waitcnt lgkmcnt(0)
	s_barrier
	s_waitcnt lgkmcnt(0)
	v_mfma_f32_16x16x32_bf16 v[126:129], v[144:147], v[176:179], v[126:129]
	v_mfma_f32_16x16x32_bf16 v[122:125], v[152:155], v[176:179], v[122:125]
	v_mfma_f32_16x16x32_bf16 v[110:113], v[144:147], v[184:187], v[110:113]
	v_mfma_f32_16x16x32_bf16 v[106:109], v[152:155], v[184:187], v[106:109]
	v_mfma_f32_16x16x32_bf16 v[94:97], v[144:147], v[198:201], v[94:97]
	v_mfma_f32_16x16x32_bf16 v[90:93], v[152:155], v[198:201], v[90:93]
	v_mfma_f32_16x16x32_bf16 v[78:81], v[144:147], v[214:217], v[78:81]
	v_mfma_f32_16x16x32_bf16 v[74:77], v[152:155], v[214:217], v[74:77]
	v_mfma_f32_16x16x32_bf16 v[126:129], v[148:151], v[180:183], v[126:129]
	v_mfma_f32_16x16x32_bf16 v[122:125], v[156:159], v[180:183], v[122:125]
	v_mfma_f32_16x16x32_bf16 v[110:113], v[148:151], v[194:197], v[110:113]
	v_mfma_f32_16x16x32_bf16 v[106:109], v[156:159], v[194:197], v[106:109]
	v_mfma_f32_16x16x32_bf16 v[94:97], v[148:151], v[204:207], v[94:97]
	v_mfma_f32_16x16x32_bf16 v[90:93], v[156:159], v[204:207], v[90:93]
	v_mfma_f32_16x16x32_bf16 v[78:81], v[148:151], v[218:221], v[78:81]
	v_mfma_f32_16x16x32_bf16 v[74:77], v[156:159], v[218:221], v[74:77]
	v_mfma_f32_16x16x32_bf16 v[118:121], v[160:163], v[176:179], v[118:121]
	v_mfma_f32_16x16x32_bf16 v[114:117], v[168:171], v[176:179], v[114:117]
	v_mfma_f32_16x16x32_bf16 v[102:105], v[160:163], v[184:187], v[102:105]
	v_mfma_f32_16x16x32_bf16 v[98:101], v[168:171], v[184:187], v[98:101]
	v_mfma_f32_16x16x32_bf16 v[86:89], v[160:163], v[198:201], v[86:89]
	v_mfma_f32_16x16x32_bf16 v[82:85], v[168:171], v[198:201], v[82:85]
	v_mfma_f32_16x16x32_bf16 v[70:73], v[160:163], v[214:217], v[70:73]
	v_mfma_f32_16x16x32_bf16 v[66:69], v[168:171], v[214:217], v[66:69]
	v_mfma_f32_16x16x32_bf16 v[118:121], v[164:167], v[180:183], v[118:121]
	v_mfma_f32_16x16x32_bf16 v[114:117], v[172:175], v[180:183], v[114:117]
	v_mfma_f32_16x16x32_bf16 v[102:105], v[164:167], v[194:197], v[102:105]
	v_mfma_f32_16x16x32_bf16 v[98:101], v[172:175], v[194:197], v[98:101]
	v_mfma_f32_16x16x32_bf16 v[86:89], v[164:167], v[204:207], v[86:89]
	v_mfma_f32_16x16x32_bf16 v[82:85], v[172:175], v[204:207], v[82:85]
	v_mfma_f32_16x16x32_bf16 v[70:73], v[164:167], v[218:221], v[70:73]
	v_mfma_f32_16x16x32_bf16 v[66:69], v[172:175], v[218:221], v[66:69]
	s_barrier
	s_add_i32 s8, s11, s74
	v_lshl_add_u64 v[188:189], v[188:189], 0, s[30:31]
	s_mov_b32 m0, s8
	ds_read_b128 v[176:179], v193 offset:49152
	ds_read_b128 v[180:183], v193 offset:50176
	ds_read_b128 v[184:187], v193 offset:51200
	ds_read_b128 v[194:197], v193 offset:52224
	ds_read_b128 v[198:201], v193 offset:53248
	ds_read_b128 v[204:207], v193 offset:54272
	ds_read_b128 v[214:217], v193 offset:55296
	ds_read_b128 v[218:221], v193 offset:56320
	global_load_lds_dwordx4 v[188:189], off
	v_lshl_add_u64 v[188:189], v[222:223], 0, s[30:31]
	s_add_i32 m0, s8, 0x2000
	s_add_i32 s8, s17, s74
	global_load_lds_dwordx4 v[188:189], off
	v_lshl_add_u64 v[188:189], v[224:225], 0, s[30:31]
	s_mov_b32 m0, s8
	s_nop 0
	global_load_lds_dwordx4 v[188:189], off
	v_lshl_add_u64 v[188:189], v[226:227], 0, s[30:31]
	s_add_i32 m0, s8, 0x2000
	s_nop 0
	global_load_lds_dwordx4 v[188:189], off
	v_lshl_add_u64 v[188:189], v[228:229], 0, s[30:31]
	s_mov_b32 m0, s63
	s_nop 0
	global_load_lds_dwordx4 v[188:189], off
	v_lshl_add_u64 v[188:189], v[230:231], 0, s[30:31]
	s_mov_b32 m0, s44
	s_nop 0
	global_load_lds_dwordx4 v[188:189], off
	s_waitcnt vmcnt(8)
	s_waitcnt lgkmcnt(0)
	s_barrier
	s_waitcnt lgkmcnt(0)
	v_mfma_f32_16x16x32_bf16 v[62:65], v[144:147], v[176:179], v[62:65]
	v_mfma_f32_16x16x32_bf16 v[58:61], v[152:155], v[176:179], v[58:61]
	v_mfma_f32_16x16x32_bf16 v[46:49], v[144:147], v[184:187], v[46:49]
	v_mfma_f32_16x16x32_bf16 v[42:45], v[152:155], v[184:187], v[42:45]
	v_mfma_f32_16x16x32_bf16 v[30:33], v[144:147], v[198:201], v[30:33]
	v_mfma_f32_16x16x32_bf16 v[26:29], v[152:155], v[198:201], v[26:29]
	v_mfma_f32_16x16x32_bf16 v[14:17], v[144:147], v[214:217], v[14:17]
	v_mfma_f32_16x16x32_bf16 v[10:13], v[152:155], v[214:217], v[10:13]
	v_mfma_f32_16x16x32_bf16 v[62:65], v[148:151], v[180:183], v[62:65]
	v_mfma_f32_16x16x32_bf16 v[58:61], v[156:159], v[180:183], v[58:61]
	v_mfma_f32_16x16x32_bf16 v[46:49], v[148:151], v[194:197], v[46:49]
	v_mfma_f32_16x16x32_bf16 v[42:45], v[156:159], v[194:197], v[42:45]
	v_mfma_f32_16x16x32_bf16 v[30:33], v[148:151], v[204:207], v[30:33]
	v_mfma_f32_16x16x32_bf16 v[26:29], v[156:159], v[204:207], v[26:29]
	v_mfma_f32_16x16x32_bf16 v[14:17], v[148:151], v[218:221], v[14:17]
	v_mfma_f32_16x16x32_bf16 v[10:13], v[156:159], v[218:221], v[10:13]
	v_mfma_f32_16x16x32_bf16 v[54:57], v[160:163], v[176:179], v[54:57]
	v_mfma_f32_16x16x32_bf16 v[50:53], v[168:171], v[176:179], v[50:53]
	v_mfma_f32_16x16x32_bf16 v[38:41], v[160:163], v[184:187], v[38:41]
	v_mfma_f32_16x16x32_bf16 v[34:37], v[168:171], v[184:187], v[34:37]
	v_mfma_f32_16x16x32_bf16 v[22:25], v[160:163], v[198:201], v[22:25]
	v_mfma_f32_16x16x32_bf16 v[18:21], v[168:171], v[198:201], v[18:21]
	v_mfma_f32_16x16x32_bf16 v[6:9], v[160:163], v[214:217], v[6:9]
	v_mfma_f32_16x16x32_bf16 v[2:5], v[168:171], v[214:217], v[2:5]
	v_mfma_f32_16x16x32_bf16 v[54:57], v[164:167], v[180:183], v[54:57]
	v_mfma_f32_16x16x32_bf16 v[50:53], v[172:175], v[180:183], v[50:53]
	v_mfma_f32_16x16x32_bf16 v[38:41], v[164:167], v[194:197], v[38:41]
	v_mfma_f32_16x16x32_bf16 v[34:37], v[172:175], v[194:197], v[34:37]
	v_mfma_f32_16x16x32_bf16 v[22:25], v[164:167], v[204:207], v[22:25]
	v_mfma_f32_16x16x32_bf16 v[18:21], v[172:175], v[204:207], v[18:21]
	v_mfma_f32_16x16x32_bf16 v[6:9], v[164:167], v[218:221], v[6:9]
	v_mfma_f32_16x16x32_bf16 v[2:5], v[172:175], v[218:221], v[2:5]
	s_barrier
	s_add_u32 s15, s15, 0x100
	s_addc_u32 s16, s16, 0
	s_add_u32 s6, s6, 0x100
	s_addc_u32 s7, s7, 0
	s_cmp_ge_u32 s10, s47
	s_mov_b32 s8, s10
	s_cbranch_scc0 .LBB0_223
	v_readlane_b32 s6, v243, 45
	v_readlane_b32 s7, v243, 46
	s_and_b64 vcc, exec, s[6:7]
	s_cbranch_vccz .LBB0_226
	s_barrier

.LBB0_1295:
	s_setprio 0
	s_waitcnt vmcnt(0)
	v_readlane_b32 s88, v243, 19
	v_readlane_b32 s89, v243, 20
	v_readlane_b32 s96, v243, 23
	v_readlane_b32 s98, v243, 25
	v_readlane_b32 s20, v243, 9
	v_readlane_b32 s22, v243, 11
	v_readlane_b32 s24, v243, 13
	v_readlane_b32 s28, v243, 15
	v_readlane_b32 s34, v243, 17
	v_readlane_b32 s36, v243, 39
	v_readlane_b32 s94, v243, 21
	v_readlane_b32 s95, v243, 22
	v_readlane_b32 s97, v243, 24
	v_readlane_b32 s99, v243, 26
	v_readlane_b32 s89, v243, 27
	v_readlane_b32 s21, v243, 10
	v_readlane_b32 s23, v243, 12
	v_readlane_b32 s25, v243, 14
	v_readlane_b32 s29, v243, 16
	v_readlane_b32 s35, v243, 18
	v_readlane_b32 s37, v243, 40
	s_barrier
